# nt (streaming) cache hint on read-once loads and write-once stores: weight-transpose loads, phase-0 x loads, final phase x / y loads and out stores
# speedup vs baseline: 1.0259x; 1.0159x over previous
.LBB0_29:
	v_lshlrev_b32_e32 v0, 2, v198
	v_and_b32_e32 v0, 60, v0
	v_mov_b32_e32 v17, 0
	v_lshlrev_b32_e32 v16, 2, v0
	v_add_u32_e32 v19, 32, v18
	v_lshl_add_u64 v[0:1], s[6:7], 0, v[16:17]
	v_mul_hi_u32_u24_e32 v3, s8, v18
	v_mul_u32_u24_e32 v2, s8, v18
	v_mul_hi_u32_u24_e32 v5, s8, v19
	v_mul_u32_u24_e32 v4, s8, v19
	v_lshl_add_u64 v[2:3], v[2:3], 2, v[0:1]
	v_lshl_add_u64 v[4:5], v[4:5], 2, v[0:1]
	global_load_dwordx4 v[0:3], v[2:3], off nt
	s_nop 0
	global_load_dwordx4 v[4:7], v[4:5], off nt
	s_or_b32 s15, s0, 1
	s_cmpk_lt_i32 s15, 0x1800
	s_cbranch_scc1 .LBB0_32
	s_cmpk_lt_u32 s0, 0x1c00
	s_cbranch_scc1 .LBB0_33
	s_lshl_b32 s6, s15, 8
	s_and_b32 s6, s6, 0x1d00
	s_add_u32 s6, s13, s6
	s_addc_u32 s7, s14, 0
	s_cbranch_execz .LBB0_34
	s_branch .LBB0_35

.LBB0_37:
	v_mov_b32_e32 v17, 0
	v_lshl_add_u64 v[8:9], s[6:7], 0, v[16:17]
	v_mul_hi_u32_u24_e32 v11, s8, v18
	v_mul_u32_u24_e32 v10, s8, v18
	v_mul_hi_u32_u24_e32 v13, s8, v19
	v_mul_u32_u24_e32 v12, s8, v19
	v_lshl_add_u64 v[10:11], v[10:11], 2, v[8:9]
	v_lshl_add_u64 v[8:9], v[12:13], 2, v[8:9]
	global_load_dwordx4 v[12:15], v[10:11], off nt
	s_nop 0
	global_load_dwordx4 v[8:11], v[8:9], off nt
	s_or_b32 s15, s0, 2
	s_cmpk_lt_i32 s15, 0x1800
	s_cbranch_scc1 .LBB0_40
	s_cmpk_lt_u32 s0, 0x1c00
	s_cbranch_scc1 .LBB0_41
	s_lshl_b32 s6, s15, 8
	s_and_b32 s6, s6, 0x1e00
	s_add_u32 s6, s13, s6
	s_addc_u32 s7, s14, 0
	s_cbranch_execz .LBB0_42
	s_branch .LBB0_43

.LBB0_45:
	v_mov_b32_e32 v17, 0
	v_lshl_add_u64 v[20:21], s[6:7], 0, v[16:17]
	v_mul_hi_u32_u24_e32 v23, s8, v18
	v_mul_u32_u24_e32 v22, s8, v18
	v_lshl_add_u64 v[22:23], v[22:23], 2, v[20:21]
	v_mul_hi_u32_u24_e32 v25, s8, v19
	v_mul_u32_u24_e32 v24, s8, v19
	v_lshl_add_u64 v[20:21], v[24:25], 2, v[20:21]
	global_load_dwordx4 v[28:31], v[22:23], off nt
	global_load_dwordx4 v[24:27], v[20:21], off nt
	s_or_b32 s15, s0, 3
	s_cmpk_lt_i32 s15, 0x1800
	s_cbranch_scc1 .LBB0_48
	s_cmpk_lt_u32 s0, 0x1c00
	s_cbranch_scc1 .LBB0_49
	s_lshl_b32 s6, s15, 8
	s_and_b32 s6, s6, 0x1f00
	s_add_u32 s6, s13, s6
	s_addc_u32 s7, s14, 0
	s_cbranch_execz .LBB0_50
	s_branch .LBB0_51

.LBB0_53:
	v_mov_b32_e32 v17, 0
	v_lshl_add_u64 v[16:17], s[6:7], 0, v[16:17]
	v_mul_hi_u32_u24_e32 v21, s4, v18
	v_mul_u32_u24_e32 v20, s4, v18
	v_lshl_add_u64 v[20:21], v[20:21], 2, v[16:17]
	v_mul_hi_u32_u24_e32 v23, s4, v19
	v_mul_u32_u24_e32 v22, s4, v19
	v_lshl_add_u64 v[16:17], v[22:23], 2, v[16:17]
	global_load_dwordx4 v[44:47], v[20:21], off nt
	global_load_dwordx4 v[40:43], v[16:17], off nt

.LBB0_66:
	v_lshlrev_b32_e32 v66, 2, v64
	v_lshl_add_u64 v[16:17], s[8:9], 0, v[66:67]
	v_mul_hi_u32_u24_e32 v19, s10, v136
	v_mul_u32_u24_e32 v18, s10, v136
	v_mul_hi_u32_u24_e32 v21, s10, v69
	v_mul_u32_u24_e32 v20, s10, v69
	v_lshl_add_u64 v[18:19], v[18:19], 2, v[16:17]
	v_lshl_add_u64 v[20:21], v[20:21], 2, v[16:17]
	global_load_dwordx4 v[16:19], v[18:19], off nt
	s_nop 0
	global_load_dwordx4 v[20:23], v[20:21], off nt
	s_add_i32 s24, s18, 1
	s_cmpk_lt_i32 s24, 0x1800
	s_mov_b64 s[10:11], -1
	s_cbranch_scc1 .LBB0_72
	s_cmpk_lt_u32 s18, 0x1c00
	s_cbranch_scc1 .LBB0_69
	s_add_i32 s8, s13, s12
	s_add_i32 s8, s8, 64
	s_and_b32 s8, s8, 0x740
	s_lshl_b32 s8, s8, 2
	s_add_u32 s8, s22, s8
	s_addc_u32 s9, s23, 0
	s_mov_b64 s[10:11], 0

.LBB0_74:
	v_lshl_add_u64 v[32:33], s[8:9], 0, v[66:67]
	v_mul_hi_u32_u24_e32 v35, s10, v136
	v_mul_u32_u24_e32 v34, s10, v136
	v_mul_hi_u32_u24_e32 v37, s10, v69
	v_mul_u32_u24_e32 v36, s10, v69
	v_lshl_add_u64 v[34:35], v[34:35], 2, v[32:33]
	v_lshl_add_u64 v[36:37], v[36:37], 2, v[32:33]
	global_load_dwordx4 v[32:35], v[34:35], off nt
	s_nop 0
	global_load_dwordx4 v[36:39], v[36:37], off nt
	s_add_i32 s24, s18, 2
	s_cmpk_lt_i32 s24, 0x1800
	s_mov_b64 s[10:11], -1
	s_cbranch_scc1 .LBB0_80
	s_cmpk_lt_u32 s18, 0x1c00
	s_cbranch_scc1 .LBB0_77
	s_add_i32 s8, s13, s12
	s_addk_i32 s8, 0x80
	s_and_b32 s8, s8, 0x780
	s_lshl_b32 s8, s8, 2
	s_add_u32 s8, s22, s8
	s_addc_u32 s9, s23, 0
	s_mov_b64 s[10:11], 0

.LBB0_82:
	v_lshl_add_u64 v[48:49], s[8:9], 0, v[66:67]
	v_mul_hi_u32_u24_e32 v51, s10, v136
	v_mul_u32_u24_e32 v50, s10, v136
	v_mul_hi_u32_u24_e32 v53, s10, v69
	v_mul_u32_u24_e32 v52, s10, v69
	v_lshl_add_u64 v[50:51], v[50:51], 2, v[48:49]
	v_lshl_add_u64 v[52:53], v[52:53], 2, v[48:49]
	global_load_dwordx4 v[48:51], v[50:51], off nt
	s_nop 0
	global_load_dwordx4 v[52:55], v[52:53], off nt
	s_add_i32 s24, s18, 3
	s_cmpk_lt_i32 s24, 0x1800
	s_mov_b64 s[10:11], -1
	s_cbranch_scc1 .LBB0_88
	s_cmpk_lt_u32 s18, 0x1c00
	s_cbranch_scc1 .LBB0_85
	s_add_i32 s8, s13, s12
	s_addk_i32 s8, 0xc0
	s_and_b32 s8, s8, 0x7c0
	s_lshl_b32 s8, s8, 2
	s_add_u32 s8, s22, s8
	s_addc_u32 s9, s23, 0
	s_mov_b64 s[10:11], 0

.LBB0_90:
	v_lshl_add_u64 v[56:57], s[8:9], 0, v[66:67]
	v_mul_hi_u32_u24_e32 v59, s6, v136
	v_mul_u32_u24_e32 v58, s6, v136
	v_mul_hi_u32_u24_e32 v61, s6, v69
	v_mul_u32_u24_e32 v60, s6, v69
	v_lshl_add_u64 v[58:59], v[58:59], 2, v[56:57]
	v_lshl_add_u64 v[60:61], v[60:61], 2, v[56:57]
	global_load_dwordx4 v[56:59], v[58:59], off nt
	s_nop 0
	global_load_dwordx4 v[60:63], v[60:61], off nt
	v_readlane_b32 s72, v236, 22
	v_readlane_b32 s73, v236, 23
	v_readlane_b32 s74, v236, 24
	v_readlane_b32 s75, v236, 25
	v_readlane_b32 s76, v236, 26
	v_readlane_b32 s77, v236, 27
	v_readlane_b32 s80, v236, 30
	v_readlane_b32 s81, v236, 31
	v_readlane_b32 s82, v236, 32
	v_readlane_b32 s83, v236, 33
	v_readlane_b32 s84, v236, 34
	v_readlane_b32 s85, v236, 35
	v_readlane_b32 s86, v236, 36
	v_readlane_b32 s87, v236, 37
	v_readlane_b32 s78, v236, 28
	v_readlane_b32 s79, v236, 29

.Lp0_nokm:
	v_lshrrev_b32_e32 v0, 2, v198
	s_mov_b32 s20, 0xc040
	v_mul_lo_u32 v0, v0, s20
	v_and_b32_e32 v1, 3, v198
	v_lshl_add_u32 v0, v1, 4, v0
	s_add_u32 s18, s10, 0x4000
	s_addc_u32 s19, s11, 0
	global_load_dwordx4 v[4:7], v0, s[18:19]
	s_add_u32 s18, s18, 0x602000
	s_addc_u32 s19, s19, 0
	global_load_dwordx4 v[8:11], v0, s[18:19]
	s_add_u32 s18, s18, 0x602000
	s_addc_u32 s19, s19, 0
	global_load_dwordx4 v[12:15], v0, s[18:19]
	s_add_u32 s18, s18, 0x602000
	s_addc_u32 s19, s19, 0
	global_load_dwordx4 v[16:19], v0, s[18:19]
	s_add_u32 s18, s18, 0x602000
	s_addc_u32 s19, s19, 0
	global_load_dwordx4 v[20:23], v0, s[18:19]
	s_add_u32 s18, s18, 0x602000
	s_addc_u32 s19, s19, 0
	global_load_dwordx4 v[24:27], v0, s[18:19]
	s_add_u32 s18, s18, 0x602000
	s_addc_u32 s19, s19, 0
	global_load_dwordx4 v[28:31], v0, s[18:19]
	s_add_u32 s18, s18, 0x602000
	s_addc_u32 s19, s19, 0
	global_load_dwordx4 v[32:35], v0, s[18:19]
	s_add_u32 s18, s18, 0x602000
	s_addc_u32 s19, s19, 0
	global_load_dwordx4 v[36:39], v0, s[18:19]
	s_add_u32 s18, s18, 0x602000
	s_addc_u32 s19, s19, 0
	global_load_dwordx4 v[40:43], v0, s[18:19]
	s_add_u32 s18, s18, 0x602000
	s_addc_u32 s19, s19, 0
	global_load_dwordx4 v[44:47], v0, s[18:19]
	s_add_u32 s18, s18, 0x602000
	s_addc_u32 s19, s19, 0
	global_load_dwordx4 v[48:51], v0, s[18:19]
	s_add_u32 s18, s18, 0x602000
	s_addc_u32 s19, s19, 0
	global_load_dwordx4 v[52:55], v0, s[18:19]
	s_add_u32 s18, s18, 0x602000
	s_addc_u32 s19, s19, 0
	global_load_dwordx4 v[56:59], v0, s[18:19]
	s_add_u32 s18, s18, 0x602000
	s_addc_u32 s19, s19, 0
	global_load_dwordx4 v[60:63], v0, s[18:19]
	s_add_u32 s18, s18, 0x602000
	s_addc_u32 s19, s19, 0
	global_load_dwordx4 v[64:67], v0, s[18:19]
	s_add_u32 s32, s8, 0x1000
	s_addc_u32 s33, s9, 0
	global_load_dwordx4 v[200:203], v166, s[8:9] offset:0
	global_load_dwordx4 v[204:207], v166, s[8:9] offset:1024
	global_load_dwordx4 v[208:211], v166, s[8:9] offset:2048
	global_load_dwordx4 v[212:215], v166, s[8:9] offset:3072
	global_load_dwordx4 v[216:219], v166, s[32:33] offset:0
	global_load_dwordx4 v[220:223], v166, s[32:33] offset:1024
	global_load_dwordx4 v[224:227], v166, s[32:33] offset:2048
	global_load_dwordx4 v[228:231], v166, s[32:33] offset:3072
	v_bfe_u32 v2, v198, 2, 2
	v_lshrrev_b32_e32 v3, 4, v198
	v_lshl_add_u32 v2, v2, 6, v3
	v_lshlrev_b32_e32 v2, 6, v2
	v_add_u32_e32 v3, v1, v196
	v_and_b32_e32 v3, 3, v3
	v_lshl_add_u32 v2, v3, 4, v2
	s_waitcnt vmcnt(23)
	ds_write_b128 v2, v[4:7] offset:0
	s_waitcnt vmcnt(22)
	ds_write_b128 v2, v[8:11] offset:2048
	s_waitcnt vmcnt(21)
	ds_write_b128 v2, v[12:15] offset:16384
	s_waitcnt vmcnt(20)
	ds_write_b128 v2, v[16:19] offset:18432
	s_waitcnt vmcnt(19)
	ds_write_b128 v2, v[20:23] offset:32768
	s_waitcnt vmcnt(18)
	ds_write_b128 v2, v[24:27] offset:34816
	s_waitcnt vmcnt(17)
	ds_write_b128 v2, v[28:31] offset:49152
	s_waitcnt vmcnt(16)
	ds_write_b128 v2, v[32:35] offset:51200
	s_waitcnt vmcnt(15)
	v_add_u32_e32 v3, 0x10000, v2
	ds_write_b128 v3, v[36:39] offset:0
	s_waitcnt vmcnt(14)
	ds_write_b128 v3, v[40:43] offset:2048
	s_waitcnt vmcnt(13)
	ds_write_b128 v3, v[44:47] offset:16384
	s_waitcnt vmcnt(12)
	ds_write_b128 v3, v[48:51] offset:18432
	s_waitcnt vmcnt(11)
	ds_write_b128 v3, v[52:55] offset:32768
	s_waitcnt vmcnt(10)
	ds_write_b128 v3, v[56:59] offset:34816
	s_waitcnt vmcnt(9)
	ds_write_b128 v3, v[60:63] offset:49152
	s_waitcnt vmcnt(8)
	ds_write_b128 v3, v[64:67] offset:51200
	v_lshrrev_b32_e32 v0, 2, v197
	v_add_u32_e32 v1, 0, v0
	v_and_b32_e32 v1, 3, v1
	v_lshlrev_b32_e32 v1, 4, v1
	v_lshl_add_u32 v244, v197, 6, v1
	v_add_u32_e32 v248, 0x10000, v244
	v_add_u32_e32 v1, 1, v0
	v_and_b32_e32 v1, 3, v1
	v_lshlrev_b32_e32 v1, 4, v1
	v_lshl_add_u32 v245, v197, 6, v1
	v_add_u32_e32 v249, 0x10000, v245
	v_add_u32_e32 v1, 2, v0
	v_and_b32_e32 v1, 3, v1
	v_lshlrev_b32_e32 v1, 4, v1
	v_lshl_add_u32 v246, v197, 6, v1
	v_add_u32_e32 v250, 0x10000, v246
	v_add_u32_e32 v1, 3, v0
	v_and_b32_e32 v1, 3, v1
	v_lshlrev_b32_e32 v1, 4, v1
	v_lshl_add_u32 v247, v197, 6, v1
	v_add_u32_e32 v251, 0x10000, v247
	v_and_b32_e32 v0, 32, v197
	v_cmp_ne_u32_e64 s[24:25], 0, v0
	v_and_b32_e32 v0, 16, v197
	v_cmp_ne_u32_e64 s[26:27], 0, v0
	v_and_b32_e32 v0, 8, v197
	v_cmp_ne_u32_e64 s[28:29], 0, v0
	v_and_b32_e32 v0, 4, v197
	v_cmp_ne_u32_e64 s[30:31], 0, v0
	v_and_b32_e32 v0, 2, v197
	v_cmp_ne_u32_e64 s[34:35], 0, v0
	v_bfe_u32 v0, v197, 1, 3
	v_lshlrev_b32_e32 v0, 2, v0
	global_load_dword v237, v0, s[36:37]
	global_load_dword v195, v0, s[38:39]
	s_waitcnt vmcnt(0) lgkmcnt(0)
	v_mul_f32_e32 v237, 0x3fb8aa3b, v237
	v_exp_f32_e32 v237, v237
	s_mov_b32 s20, 0x3a000000
	s_barrier
	v_readfirstlane_b32 s18, v196
	s_lshl_b32 s16, s96, 6
	s_lshl_b32 s18, s18, 3
	s_add_u32 s16, s16, s18
	s_lshl_b32 s18, s16, 13
	s_add_u32 s22, s4, s18
	s_addc_u32 s23, s5, 0
	s_add_u32 s32, s22, 0x1000
	s_addc_u32 s33, s23, 0
	global_load_dwordx4 v[64:67], v166, s[22:23] offset:0 nt
	global_load_dwordx4 v[68:71], v166, s[22:23] offset:1024 nt
	global_load_dwordx4 v[72:75], v166, s[22:23] offset:2048 nt
	global_load_dwordx4 v[76:79], v166, s[22:23] offset:3072 nt
	global_load_dwordx4 v[80:83], v166, s[32:33] offset:0 nt
	global_load_dwordx4 v[84:87], v166, s[32:33] offset:1024 nt
	global_load_dwordx4 v[88:91], v166, s[32:33] offset:2048 nt
	global_load_dwordx4 v[92:95], v166, s[32:33] offset:3072 nt
	s_add_u32 s22, s22, 0x2000
	s_addc_u32 s23, s23, 0
	s_add_u32 s32, s22, 0x1000
	s_addc_u32 s33, s23, 0
	global_load_dwordx4 v[96:99], v166, s[22:23] offset:0 nt
	global_load_dwordx4 v[100:103], v166, s[22:23] offset:1024 nt
	global_load_dwordx4 v[104:107], v166, s[22:23] offset:2048 nt
	global_load_dwordx4 v[108:111], v166, s[22:23] offset:3072 nt
	global_load_dwordx4 v[112:115], v166, s[32:33] offset:0 nt
	global_load_dwordx4 v[116:119], v166, s[32:33] offset:1024 nt
	global_load_dwordx4 v[120:123], v166, s[32:33] offset:2048 nt
	global_load_dwordx4 v[124:127], v166, s[32:33] offset:3072 nt
	s_mov_b32 s17, 0

.Lp0_cp:
	v_mov_b32_e32 v0, v64
	v_mov_b32_e32 v1, v65
	v_mov_b32_e32 v2, v66
	v_mov_b32_e32 v3, v67
	v_mov_b32_e32 v4, v68
	v_mov_b32_e32 v5, v69
	v_mov_b32_e32 v6, v70
	v_mov_b32_e32 v7, v71
	v_mov_b32_e32 v8, v72
	v_mov_b32_e32 v9, v73
	v_mov_b32_e32 v10, v74
	v_mov_b32_e32 v11, v75
	v_mov_b32_e32 v12, v76
	v_mov_b32_e32 v13, v77
	v_mov_b32_e32 v14, v78
	v_mov_b32_e32 v15, v79
	v_mov_b32_e32 v16, v80
	v_mov_b32_e32 v17, v81
	v_mov_b32_e32 v18, v82
	v_mov_b32_e32 v19, v83
	v_mov_b32_e32 v20, v84
	v_mov_b32_e32 v21, v85
	v_mov_b32_e32 v22, v86
	v_mov_b32_e32 v23, v87
	v_mov_b32_e32 v24, v88
	v_mov_b32_e32 v25, v89
	v_mov_b32_e32 v26, v90
	v_mov_b32_e32 v27, v91
	v_mov_b32_e32 v28, v92
	v_mov_b32_e32 v29, v93
	v_mov_b32_e32 v30, v94
	v_mov_b32_e32 v31, v95
	v_mov_b32_e32 v32, v96
	v_mov_b32_e32 v33, v97
	v_mov_b32_e32 v34, v98
	v_mov_b32_e32 v35, v99
	v_mov_b32_e32 v36, v100
	v_mov_b32_e32 v37, v101
	v_mov_b32_e32 v38, v102
	v_mov_b32_e32 v39, v103
	v_mov_b32_e32 v40, v104
	v_mov_b32_e32 v41, v105
	v_mov_b32_e32 v42, v106
	v_mov_b32_e32 v43, v107
	v_mov_b32_e32 v44, v108
	v_mov_b32_e32 v45, v109
	v_mov_b32_e32 v46, v110
	v_mov_b32_e32 v47, v111
	v_mov_b32_e32 v48, v112
	v_mov_b32_e32 v49, v113
	v_mov_b32_e32 v50, v114
	v_mov_b32_e32 v51, v115
	v_mov_b32_e32 v52, v116
	v_mov_b32_e32 v53, v117
	v_mov_b32_e32 v54, v118
	v_mov_b32_e32 v55, v119
	v_mov_b32_e32 v56, v120
	v_mov_b32_e32 v57, v121
	v_mov_b32_e32 v58, v122
	v_mov_b32_e32 v59, v123
	v_mov_b32_e32 v60, v124
	v_mov_b32_e32 v61, v125
	v_mov_b32_e32 v62, v126
	v_mov_b32_e32 v63, v127
	s_cmp_ge_u32 s17, 3
	s_cbranch_scc1 .Lp0_nopf
	s_add_u32 s16, s16, 2
	s_lshl_b32 s18, s16, 13
	s_add_u32 s22, s4, s18
	s_addc_u32 s23, s5, 0
	s_add_u32 s32, s22, 0x1000
	s_addc_u32 s33, s23, 0
	global_load_dwordx4 v[64:67], v166, s[22:23] offset:0 nt
	global_load_dwordx4 v[68:71], v166, s[22:23] offset:1024 nt
	global_load_dwordx4 v[72:75], v166, s[22:23] offset:2048 nt
	global_load_dwordx4 v[76:79], v166, s[22:23] offset:3072 nt
	global_load_dwordx4 v[80:83], v166, s[32:33] offset:0 nt
	global_load_dwordx4 v[84:87], v166, s[32:33] offset:1024 nt
	global_load_dwordx4 v[88:91], v166, s[32:33] offset:2048 nt
	global_load_dwordx4 v[92:95], v166, s[32:33] offset:3072 nt
	s_add_u32 s22, s22, 0x2000
	s_addc_u32 s23, s23, 0
	s_add_u32 s32, s22, 0x1000
	s_addc_u32 s33, s23, 0
	global_load_dwordx4 v[96:99], v166, s[22:23] offset:0 nt
	global_load_dwordx4 v[100:103], v166, s[22:23] offset:1024 nt
	global_load_dwordx4 v[104:107], v166, s[22:23] offset:2048 nt
	global_load_dwordx4 v[108:111], v166, s[22:23] offset:3072 nt
	global_load_dwordx4 v[112:115], v166, s[32:33] offset:0 nt
	global_load_dwordx4 v[116:119], v166, s[32:33] offset:1024 nt
	global_load_dwordx4 v[120:123], v166, s[32:33] offset:2048 nt
	global_load_dwordx4 v[124:127], v166, s[32:33] offset:3072 nt
	s_sub_u32 s16, s16, 2

.LBB0_944:
	s_or_b64 exec, exec, s[0:1]
	v_lshlrev_b64 v[30:31], 12, v[0:1]
	v_readlane_b32 s8, v236, 3
	v_lshl_add_u64 v[38:39], v[16:17], 0, v[30:31]
	v_lshlrev_b64 v[42:43], 13, v[0:1]
	v_readlane_b32 s9, v236, 4
	global_load_dwordx2 v[40:41], v[38:39], off nt
	global_load_dwordx4 v[30:33], v[6:7], off
	v_lshl_add_u64 v[44:45], s[8:9], 0, v[42:43]
	v_lshl_add_u64 v[46:47], v[44:45], 0, v[2:3]
	global_load_dwordx4 v[34:37], v[46:47], off nt
	s_waitcnt vmcnt(3)
	ds_bpermute_b32 v1, v202, v28
	v_lshl_add_u64 v[42:43], s[62:63], 0, v[42:43]
	v_lshl_add_u64 v[48:49], v[42:43], 0, v[2:3]
	v_add_u32_e32 v0, s4, v0
	v_readlane_b32 s10, v236, 5
	s_waitcnt lgkmcnt(0)
	v_add_f32_e32 v1, v28, v1
	ds_bpermute_b32 v28, v201, v1
	v_readlane_b32 s11, v236, 6
	v_readlane_b32 s12, v236, 7
	v_readlane_b32 s13, v236, 8
	v_readlane_b32 s14, v236, 9
	s_waitcnt lgkmcnt(0)
	v_add_f32_e32 v1, v1, v28
	ds_bpermute_b32 v28, v26, v1
	v_readlane_b32 s15, v236, 10
	v_readlane_b32 s16, v236, 11
	v_readlane_b32 s17, v236, 12
	v_readlane_b32 s18, v236, 13
	s_waitcnt lgkmcnt(0)
	v_add_f32_e32 v1, v1, v28
	ds_bpermute_b32 v28, v203, v1
	v_readlane_b32 s19, v236, 14
	v_readlane_b32 s20, v236, 15
	v_readlane_b32 s21, v236, 16
	v_readlane_b32 s22, v236, 17
	s_waitcnt lgkmcnt(0)
	v_add_f32_e32 v1, v1, v28
	ds_bpermute_b32 v28, v200, v1
	v_readlane_b32 s23, v236, 18
	s_waitcnt lgkmcnt(0)
	v_add_f32_e32 v1, v1, v28
	ds_bpermute_b32 v28, v199, v1
	s_waitcnt lgkmcnt(0)
	v_add_f32_e32 v1, v1, v28
	v_fmamk_f32 v1, v1, 0x3a000000, v27
	v_mul_f32_e32 v28, 0x4b800000, v1
	v_cmp_gt_f32_e64 s[0:1], s5, v1
	s_waitcnt vmcnt(2)
	v_and_b32_e32 v29, 0xffff0000, v40
	v_cndmask_b32_e64 v1, v1, v28, s[0:1]
	v_rsq_f32_e32 v1, v1
	s_nop 0
	v_mul_f32_e32 v28, 0x45800000, v1
	v_cndmask_b32_e64 v50, v1, v28, s[0:1]
	v_lshlrev_b32_e32 v28, 16, v40
	v_lshlrev_b32_e32 v40, 16, v41
	v_and_b32_e32 v41, 0xffff0000, v41
	v_pk_mul_f32 v[28:29], v[50:51], v[28:29] op_sel_hi:[0,1]
	v_pk_mul_f32 v[40:41], v[50:51], v[40:41] op_sel_hi:[0,1]
	s_waitcnt vmcnt(0)
	v_pk_fma_f32 v[28:29], v[30:31], v[28:29], v[34:35]
	v_pk_fma_f32 v[30:31], v[32:33], v[40:41], v[36:37]
	global_store_dwordx4 v[48:49], v[28:31], off nt
	global_load_dwordx2 v[36:37], v[38:39], off offset:512 nt
	s_nop 0
	global_load_dwordx4 v[28:31], v[46:47], off offset:1024 nt
	global_load_dwordx4 v[32:35], v[6:7], off offset:1024
	v_cmp_lt_i32_e64 s[0:1], s6, v0
	s_or_b64 s[2:3], s[0:1], s[2:3]
	s_waitcnt vmcnt(2)
	v_lshlrev_b32_e32 v40, 16, v36
	v_and_b32_e32 v41, 0xffff0000, v36
	v_lshlrev_b32_e32 v36, 16, v37
	v_and_b32_e32 v37, 0xffff0000, v37
	v_pk_mul_f32 v[40:41], v[50:51], v[40:41] op_sel_hi:[0,1]
	v_pk_mul_f32 v[36:37], v[50:51], v[36:37] op_sel_hi:[0,1]
	s_waitcnt vmcnt(0)
	v_pk_fma_f32 v[28:29], v[32:33], v[40:41], v[28:29]
	v_pk_fma_f32 v[30:31], v[34:35], v[36:37], v[30:31]
	global_store_dwordx4 v[48:49], v[28:31], off offset:1024 nt
	global_load_dwordx2 v[36:37], v[38:39], off offset:1024 nt
	s_nop 0
	global_load_dwordx4 v[28:31], v[46:47], off offset:2048 nt
	global_load_dwordx4 v[32:35], v[6:7], off offset:2048
	s_waitcnt vmcnt(2)
	v_lshlrev_b32_e32 v40, 16, v36
	v_and_b32_e32 v41, 0xffff0000, v36
	v_lshlrev_b32_e32 v36, 16, v37
	v_and_b32_e32 v37, 0xffff0000, v37
	v_pk_mul_f32 v[40:41], v[50:51], v[40:41] op_sel_hi:[0,1]
	v_pk_mul_f32 v[36:37], v[50:51], v[36:37] op_sel_hi:[0,1]
	s_waitcnt vmcnt(0)
	v_pk_fma_f32 v[28:29], v[32:33], v[40:41], v[28:29]
	v_pk_fma_f32 v[30:31], v[34:35], v[36:37], v[30:31]
	global_store_dwordx4 v[48:49], v[28:31], off offset:2048 nt
	global_load_dwordx2 v[36:37], v[38:39], off offset:1536 nt
	s_nop 0
	global_load_dwordx4 v[28:31], v[46:47], off offset:3072 nt
	global_load_dwordx4 v[32:35], v[6:7], off offset:3072
	s_waitcnt vmcnt(2)
	v_lshlrev_b32_e32 v40, 16, v36
	v_and_b32_e32 v41, 0xffff0000, v36
	v_lshlrev_b32_e32 v36, 16, v37
	v_and_b32_e32 v37, 0xffff0000, v37
	v_pk_mul_f32 v[40:41], v[50:51], v[40:41] op_sel_hi:[0,1]
	v_pk_mul_f32 v[36:37], v[50:51], v[36:37] op_sel_hi:[0,1]
	s_waitcnt vmcnt(0)
	v_pk_fma_f32 v[28:29], v[32:33], v[40:41], v[28:29]
	v_pk_fma_f32 v[30:31], v[34:35], v[36:37], v[30:31]
	global_store_dwordx4 v[48:49], v[28:31], off offset:3072 nt
	global_load_dwordx2 v[36:37], v[38:39], off offset:2048 nt
	v_lshl_add_u64 v[40:41], v[44:45], 0, v[18:19]
	global_load_dwordx4 v[28:31], v[40:41], off nt
	global_load_dwordx4 v[32:35], v[8:9], off
	v_lshl_add_u64 v[40:41], v[42:43], 0, v[18:19]
	s_waitcnt vmcnt(2)
	v_lshlrev_b32_e32 v46, 16, v36
	v_and_b32_e32 v47, 0xffff0000, v36
	v_lshlrev_b32_e32 v36, 16, v37
	v_and_b32_e32 v37, 0xffff0000, v37
	v_pk_mul_f32 v[46:47], v[50:51], v[46:47] op_sel_hi:[0,1]
	v_pk_mul_f32 v[36:37], v[50:51], v[36:37] op_sel_hi:[0,1]
	s_waitcnt vmcnt(0)
	v_pk_fma_f32 v[28:29], v[32:33], v[46:47], v[28:29]
	v_pk_fma_f32 v[30:31], v[34:35], v[36:37], v[30:31]
	global_store_dwordx4 v[40:41], v[28:31], off nt
	global_load_dwordx2 v[36:37], v[38:39], off offset:2560 nt
	v_lshl_add_u64 v[40:41], v[44:45], 0, v[20:21]
	global_load_dwordx4 v[28:31], v[40:41], off nt
	global_load_dwordx4 v[32:35], v[10:11], off
	v_lshl_add_u64 v[40:41], v[42:43], 0, v[20:21]
	s_waitcnt vmcnt(2)
	v_lshlrev_b32_e32 v46, 16, v36
	v_and_b32_e32 v47, 0xffff0000, v36
	v_lshlrev_b32_e32 v36, 16, v37
	v_and_b32_e32 v37, 0xffff0000, v37
	v_pk_mul_f32 v[46:47], v[50:51], v[46:47] op_sel_hi:[0,1]
	v_pk_mul_f32 v[36:37], v[50:51], v[36:37] op_sel_hi:[0,1]
	s_waitcnt vmcnt(0)
	v_pk_fma_f32 v[28:29], v[32:33], v[46:47], v[28:29]
	v_pk_fma_f32 v[30:31], v[34:35], v[36:37], v[30:31]
	global_store_dwordx4 v[40:41], v[28:31], off nt
	global_load_dwordx2 v[36:37], v[38:39], off offset:3072 nt
	v_lshl_add_u64 v[40:41], v[44:45], 0, v[22:23]
	global_load_dwordx4 v[28:31], v[40:41], off nt
	global_load_dwordx4 v[32:35], v[12:13], off
	v_lshl_add_u64 v[40:41], v[42:43], 0, v[22:23]
	s_waitcnt vmcnt(2)
	v_lshlrev_b32_e32 v46, 16, v36
	v_and_b32_e32 v47, 0xffff0000, v36
	v_lshlrev_b32_e32 v36, 16, v37
	v_and_b32_e32 v37, 0xffff0000, v37
	v_pk_mul_f32 v[46:47], v[50:51], v[46:47] op_sel_hi:[0,1]
	v_pk_mul_f32 v[36:37], v[50:51], v[36:37] op_sel_hi:[0,1]
	s_waitcnt vmcnt(0)
	v_pk_fma_f32 v[28:29], v[32:33], v[46:47], v[28:29]
	v_pk_fma_f32 v[30:31], v[34:35], v[36:37], v[30:31]
	global_store_dwordx4 v[40:41], v[28:31], off nt
	global_load_dwordx2 v[36:37], v[38:39], off offset:3584 nt
	v_lshl_add_u64 v[38:39], v[44:45], 0, v[24:25]
	global_load_dwordx4 v[28:31], v[38:39], off nt
	global_load_dwordx4 v[32:35], v[14:15], off
	v_lshl_add_u64 v[38:39], v[42:43], 0, v[24:25]
	s_waitcnt vmcnt(2)
	v_lshlrev_b32_e32 v40, 16, v36
	v_and_b32_e32 v41, 0xffff0000, v36
	v_lshlrev_b32_e32 v36, 16, v37
	v_and_b32_e32 v37, 0xffff0000, v37
	v_pk_mul_f32 v[40:41], v[50:51], v[40:41] op_sel_hi:[0,1]
	v_pk_mul_f32 v[36:37], v[50:51], v[36:37] op_sel_hi:[0,1]
	s_waitcnt vmcnt(0)
	v_pk_fma_f32 v[28:29], v[32:33], v[40:41], v[28:29]
	v_pk_fma_f32 v[30:31], v[34:35], v[36:37], v[30:31]
	global_store_dwordx4 v[38:39], v[28:31], off nt
	s_andn2_b64 exec, exec, s[2:3]
	s_cbranch_execz .LBB0_947
